# in-proj epilogue stores write-through (sc1) so the grid barrier's L2 writeback has little left to flush
# speedup vs baseline: 1.0150x; 1.0017x over previous
.LBB0_253:
	s_getreg_b32 s0, hwreg(HW_REG_XCC_ID, 0, 4)
	s_and_b32 s0, s0, 15
	s_lshl_b32 s0, s0, 8
	s_add_i32 s0, s0, 0x4000
	v_mov_b32_e32 v2, s0
	global_load_dword v4, v2, s[80:81] sc1
	s_waitcnt vmcnt(0)
	v_readfirstlane_b32 s0, v4
	s_nop 3
	s_bcnt1_i32_b32 s0, s0
	s_cmp_eq_u32 s0, 1
	s_cbranch_scc1 .Lxcd_chk_ok
	v_mov_b32_e32 v2, 0x5000
	v_mov_b32_e32 v4, 1
	v_cmp_eq_u32_e32 vcc, 0, v210
	s_and_saveexec_b64 s[0:1], vcc
	global_atomic_or v2, v4, s[80:81]
	s_waitcnt vmcnt(0)
	s_or_b64 exec, exec, s[0:1]

.LBB0_293:
	s_ashr_i32 s67, s29, 11
	s_mul_i32 s12, s67, 0x50
	s_lshl_b32 s65, s44, 1
	s_add_i32 s38, s12, s65
	s_ashr_i32 s39, s38, 31
	s_lshl_b64 s[46:47], s[38:39], 19
	s_add_u32 s76, s30, s46
	v_lshlrev_b32_e32 v0, 8, v0
	s_addc_u32 s77, s31, s47
	s_waitcnt lgkmcnt(0)
	v_pk_mul_f32 v[136:137], v[136:137], v[164:165] op_sel_hi:[1,0]
	v_pk_mul_f32 v[134:135], v[134:135], v[164:165] op_sel_hi:[1,0]
	v_pk_mul_f32 v[132:133], v[132:133], v[164:165] op_sel_hi:[1,0]
	v_pk_mul_f32 v[166:167], v[130:131], v[164:165] op_sel_hi:[1,0]
	v_lshl_add_u64 v[130:131], s[76:77], 0, v[0:1]
	v_mov_b32_e32 v155, v1
	v_cndmask_b32_e64 v165, 0, 1, s[48:49]
	v_cmp_ne_u32_e64 s[46:47], 1, v165
	s_andn2_b64 vcc, exec, s[48:49]
	v_lshl_add_u64 v[168:169], v[130:131], 0, v[154:155]
	s_cbranch_vccnz .LBB0_295
	v_cvt_pk_bf16_f32 v190, v134, v135
	v_cvt_pk_bf16_f32 v191, v136, v137
	v_cvt_pk_bf16_f32 v192, v166, v167
	v_cvt_pk_bf16_f32 v193, v132, v133
	global_store_dwordx4 v[168:169], v[190:193], off sc1

.LBB0_301:
	s_ashr_i32 s39, s28, 7
	s_add_i32 s4, s12, s39
	s_ashr_i32 s5, s4, 31
	s_lshl_b64 s[52:53], s[4:5], 19
	s_add_u32 s94, s30, s52
	v_cvt_pk_bf16_f32 v134, v134, v135
	v_cvt_pk_bf16_f32 v135, v136, v137
	v_cvt_pk_bf16_f32 v136, v166, v167
	v_cvt_pk_bf16_f32 v137, v132, v133
	v_mov_b32_e32 v132, v164
	v_mov_b32_e32 v133, v164
	s_addc_u32 s95, s31, s53
	v_mov_b32_e32 v165, v164
	global_store_dwordx4 v[170:171], v[134:137], off sc1
	v_pk_mul_f32 v[128:129], v[128:129], v[132:133]
	v_pk_mul_f32 v[124:125], v[124:125], v[132:133]
	v_lshl_add_u64 v[132:133], s[94:95], 0, v[0:1]
	v_mov_b32_e32 v155, v1
	v_cndmask_b32_e64 v134, 0, 1, s[54:55]
	v_pk_mul_f32 v[126:127], v[126:127], v[164:165]
	v_pk_mul_f32 v[122:123], v[122:123], v[164:165]
	v_cmp_ne_u32_e64 s[52:53], 1, v134
	s_andn2_b64 vcc, exec, s[54:55]
	v_lshl_add_u64 v[132:133], v[132:133], 0, v[154:155]
	s_cbranch_vccnz .LBB0_303
	v_cvt_pk_bf16_f32 v134, v126, v127
	v_cvt_pk_bf16_f32 v135, v128, v129
	v_cvt_pk_bf16_f32 v136, v122, v123
	v_cvt_pk_bf16_f32 v137, v124, v125
	global_store_dwordx4 v[132:133], v[134:137], off sc1

.LBB0_309:
	v_cvt_pk_bf16_f32 v126, v126, v127
	v_cvt_pk_bf16_f32 v127, v128, v129
	v_cvt_pk_bf16_f32 v128, v122, v123
	v_cvt_pk_bf16_f32 v129, v124, v125
	ds_read_b32 v122, v182 offset:64
	s_movk_i32 s5, 0x7df
	s_and_b64 vcc, exec, s[42:43]
	v_bitop3_b32 v0, v185, s5, 16 bitop3:0xc8
	global_store_dwordx4 v[134:135], v[126:129], off sc1
	s_cbranch_vccnz .LBB0_311
	v_cvt_f32_u32_e32 v53, v0
	v_mul_f32_e32 v51, v178, v53
	v_mul_f32_e32 v52, v179, v53
	v_fract_f32_e32 v51, v51
	v_fract_f32_e32 v52, v52
	v_mul_f32_e32 v50, v174, v53
	v_cos_f32_e32 v156, v51
	v_sin_f32_e32 v54, v51
	v_mul_f32_e32 v51, v175, v53
	v_cos_f32_e32 v157, v52
	v_sin_f32_e32 v55, v52
	v_mul_f32_e32 v52, v176, v53
	v_mul_f32_e32 v56, v180, v53
	v_mul_f32_e32 v57, v177, v53
	v_mul_f32_e32 v123, v181, v53
	v_fract_f32_e32 v50, v50
	v_fract_f32_e32 v51, v51
	v_fract_f32_e32 v52, v52
	v_fract_f32_e32 v56, v56
	v_fract_f32_e32 v57, v57
	v_fract_f32_e32 v123, v123
	v_cos_f32_e32 v158, v50
	v_sin_f32_e32 v50, v50
	v_cos_f32_e32 v159, v51
	v_sin_f32_e32 v51, v51
	v_cos_f32_e32 v162, v52
	v_sin_f32_e32 v52, v52
	v_cos_f32_e32 v160, v56
	v_sin_f32_e32 v56, v56
	v_sin_f32_e32 v53, v57
	v_cos_f32_e32 v163, v57
	v_sin_f32_e32 v57, v123
	v_cos_f32_e32 v161, v123
	v_pk_mul_f32 v[52:53], v[148:149], v[52:53]
	v_pk_mul_f32 v[50:51], v[146:147], v[50:51]
	v_pk_mul_f32 v[56:57], v[148:149], v[56:57]
	v_pk_mul_f32 v[54:55], v[146:147], v[54:55]
.LBB0_311:
	v_lshlrev_b32_e32 v0, 8, v0
	s_waitcnt lgkmcnt(0)
	v_pk_mul_f32 v[124:125], v[114:115], v[122:123] op_sel_hi:[1,0]
	v_lshl_add_u64 v[114:115], s[76:77], 0, v[0:1]
	v_mov_b32_e32 v155, v1
	v_pk_mul_f32 v[120:121], v[120:121], v[122:123] op_sel_hi:[1,0]
	v_pk_mul_f32 v[118:119], v[118:119], v[122:123] op_sel_hi:[1,0]
	v_pk_mul_f32 v[116:117], v[116:117], v[122:123] op_sel_hi:[1,0]
	s_and_b64 vcc, exec, s[46:47]
	v_lshl_add_u64 v[126:127], v[114:115], 0, v[154:155]
	s_cbranch_vccnz .LBB0_313
	v_cvt_pk_bf16_f32 v128, v118, v119
	v_cvt_pk_bf16_f32 v129, v120, v121
	v_cvt_pk_bf16_f32 v130, v124, v125
	v_cvt_pk_bf16_f32 v131, v116, v117
	global_store_dwordx4 v[126:127], v[128:131], off sc1

.LBB0_319:
	v_cvt_pk_bf16_f32 v118, v118, v119
	v_cvt_pk_bf16_f32 v119, v120, v121
	v_cvt_pk_bf16_f32 v120, v124, v125
	v_cvt_pk_bf16_f32 v121, v116, v117
	v_mov_b32_e32 v116, v122
	v_mov_b32_e32 v117, v122
	v_mov_b32_e32 v123, v122
	v_pk_mul_f32 v[112:113], v[112:113], v[116:117]
	v_pk_mul_f32 v[108:109], v[108:109], v[116:117]
	v_lshl_add_u64 v[116:117], s[94:95], 0, v[0:1]
	v_mov_b32_e32 v155, v1
	v_pk_mul_f32 v[110:111], v[110:111], v[122:123]
	v_pk_mul_f32 v[106:107], v[106:107], v[122:123]
	s_and_b64 vcc, exec, s[52:53]
	v_lshl_add_u64 v[116:117], v[116:117], 0, v[154:155]
	global_store_dwordx4 v[128:129], v[118:121], off sc1
	s_cbranch_vccz .LBB0_418
	s_and_b64 vcc, exec, s[54:55]
	s_cbranch_vccz .LBB0_419

.LBB0_324:
	v_cvt_pk_bf16_f32 v110, v110, v111
	v_cvt_pk_bf16_f32 v111, v112, v113
	v_cvt_pk_bf16_f32 v112, v106, v107
	v_cvt_pk_bf16_f32 v113, v108, v109
	ds_read_b32 v106, v182 offset:128
	s_movk_i32 s5, 0x7ef
	s_and_b64 vcc, exec, s[42:43]
	v_bitop3_b32 v0, v185, s5, 32 bitop3:0xc8
	global_store_dwordx4 v[118:119], v[110:113], off sc1
	s_cbranch_vccnz .LBB0_326
	v_cvt_f32_u32_e32 v53, v0
	v_mul_f32_e32 v51, v178, v53
	v_mul_f32_e32 v52, v179, v53
	v_fract_f32_e32 v51, v51
	v_fract_f32_e32 v52, v52
	v_mul_f32_e32 v50, v174, v53
	v_cos_f32_e32 v156, v51
	v_sin_f32_e32 v54, v51
	v_mul_f32_e32 v51, v175, v53
	v_cos_f32_e32 v157, v52
	v_sin_f32_e32 v55, v52
	v_mul_f32_e32 v52, v176, v53
	v_mul_f32_e32 v56, v180, v53
	v_mul_f32_e32 v57, v177, v53
	v_mul_f32_e32 v107, v181, v53
	v_fract_f32_e32 v50, v50
	v_fract_f32_e32 v51, v51
	v_fract_f32_e32 v52, v52
	v_fract_f32_e32 v56, v56
	v_fract_f32_e32 v57, v57
	v_fract_f32_e32 v107, v107
	v_cos_f32_e32 v158, v50
	v_sin_f32_e32 v50, v50
	v_cos_f32_e32 v159, v51
	v_sin_f32_e32 v51, v51
	v_cos_f32_e32 v162, v52
	v_sin_f32_e32 v52, v52
	v_cos_f32_e32 v160, v56
	v_sin_f32_e32 v56, v56
	v_sin_f32_e32 v53, v57
	v_cos_f32_e32 v163, v57
	v_sin_f32_e32 v57, v107
	v_cos_f32_e32 v161, v107
	v_pk_mul_f32 v[52:53], v[148:149], v[52:53]
	v_pk_mul_f32 v[50:51], v[146:147], v[50:51]
	v_pk_mul_f32 v[56:57], v[148:149], v[56:57]
	v_pk_mul_f32 v[54:55], v[146:147], v[54:55]
.LBB0_326:
	v_lshlrev_b32_e32 v0, 8, v0
	s_waitcnt lgkmcnt(0)
	v_pk_mul_f32 v[108:109], v[98:99], v[106:107] op_sel_hi:[1,0]
	v_lshl_add_u64 v[98:99], s[76:77], 0, v[0:1]
	v_mov_b32_e32 v155, v1
	v_pk_mul_f32 v[104:105], v[104:105], v[106:107] op_sel_hi:[1,0]
	v_pk_mul_f32 v[102:103], v[102:103], v[106:107] op_sel_hi:[1,0]
	v_pk_mul_f32 v[100:101], v[100:101], v[106:107] op_sel_hi:[1,0]
	s_and_b64 vcc, exec, s[46:47]
	v_lshl_add_u64 v[110:111], v[98:99], 0, v[154:155]
	s_cbranch_vccnz .LBB0_328
	v_cvt_pk_bf16_f32 v112, v102, v103
	v_cvt_pk_bf16_f32 v113, v104, v105
	v_cvt_pk_bf16_f32 v114, v108, v109
	v_cvt_pk_bf16_f32 v115, v100, v101
	global_store_dwordx4 v[110:111], v[112:115], off sc1

.LBB0_334:
	v_cvt_pk_bf16_f32 v102, v102, v103
	v_cvt_pk_bf16_f32 v103, v104, v105
	v_cvt_pk_bf16_f32 v104, v108, v109
	v_cvt_pk_bf16_f32 v105, v100, v101
	v_mov_b32_e32 v100, v106
	v_mov_b32_e32 v101, v106
	v_mov_b32_e32 v107, v106
	v_pk_mul_f32 v[96:97], v[96:97], v[100:101]
	v_pk_mul_f32 v[92:93], v[92:93], v[100:101]
	v_lshl_add_u64 v[100:101], s[94:95], 0, v[0:1]
	v_mov_b32_e32 v155, v1
	v_pk_mul_f32 v[94:95], v[94:95], v[106:107]
	v_pk_mul_f32 v[90:91], v[90:91], v[106:107]
	s_and_b64 vcc, exec, s[52:53]
	v_lshl_add_u64 v[100:101], v[100:101], 0, v[154:155]
	global_store_dwordx4 v[112:113], v[102:105], off sc1
	s_cbranch_vccz .LBB0_421
	s_and_b64 vcc, exec, s[54:55]
	s_cbranch_vccz .LBB0_422

.LBB0_339:
	v_cvt_pk_bf16_f32 v94, v94, v95
	v_cvt_pk_bf16_f32 v95, v96, v97
	v_cvt_pk_bf16_f32 v96, v90, v91
	v_cvt_pk_bf16_f32 v97, v92, v93
	ds_read_b32 v90, v182 offset:192
	s_and_b64 vcc, exec, s[42:43]
	v_bitop3_b32 v0, v185, s91, 48 bitop3:0xc8
	global_store_dwordx4 v[102:103], v[94:97], off sc1
	s_cbranch_vccnz .LBB0_341
	v_cvt_f32_u32_e32 v53, v0
	v_mul_f32_e32 v51, v178, v53
	v_mul_f32_e32 v52, v179, v53
	v_fract_f32_e32 v51, v51
	v_fract_f32_e32 v52, v52
	v_mul_f32_e32 v50, v174, v53
	v_cos_f32_e32 v156, v51
	v_sin_f32_e32 v54, v51
	v_mul_f32_e32 v51, v175, v53
	v_cos_f32_e32 v157, v52
	v_sin_f32_e32 v55, v52
	v_mul_f32_e32 v52, v176, v53
	v_mul_f32_e32 v56, v180, v53
	v_mul_f32_e32 v57, v177, v53
	v_mul_f32_e32 v91, v181, v53
	v_fract_f32_e32 v50, v50
	v_fract_f32_e32 v51, v51
	v_fract_f32_e32 v52, v52
	v_fract_f32_e32 v56, v56
	v_fract_f32_e32 v57, v57
	v_fract_f32_e32 v91, v91
	v_cos_f32_e32 v158, v50
	v_sin_f32_e32 v50, v50
	v_cos_f32_e32 v159, v51
	v_sin_f32_e32 v51, v51
	v_cos_f32_e32 v162, v52
	v_sin_f32_e32 v52, v52
	v_cos_f32_e32 v160, v56
	v_sin_f32_e32 v56, v56
	v_sin_f32_e32 v53, v57
	v_cos_f32_e32 v163, v57
	v_sin_f32_e32 v57, v91
	v_cos_f32_e32 v161, v91
	v_pk_mul_f32 v[52:53], v[148:149], v[52:53]
	v_pk_mul_f32 v[50:51], v[146:147], v[50:51]
	v_pk_mul_f32 v[56:57], v[148:149], v[56:57]
	v_pk_mul_f32 v[54:55], v[146:147], v[54:55]
.LBB0_341:
	v_lshlrev_b32_e32 v0, 8, v0
	s_waitcnt lgkmcnt(0)
	v_pk_mul_f32 v[92:93], v[82:83], v[90:91] op_sel_hi:[1,0]
	v_lshl_add_u64 v[82:83], s[76:77], 0, v[0:1]
	v_mov_b32_e32 v155, v1
	v_pk_mul_f32 v[88:89], v[88:89], v[90:91] op_sel_hi:[1,0]
	v_pk_mul_f32 v[86:87], v[86:87], v[90:91] op_sel_hi:[1,0]
	v_pk_mul_f32 v[84:85], v[84:85], v[90:91] op_sel_hi:[1,0]
	s_and_b64 vcc, exec, s[46:47]
	v_lshl_add_u64 v[94:95], v[82:83], 0, v[154:155]
	s_cbranch_vccnz .LBB0_343
	v_cvt_pk_bf16_f32 v96, v86, v87
	v_cvt_pk_bf16_f32 v97, v88, v89
	v_cvt_pk_bf16_f32 v98, v92, v93
	v_cvt_pk_bf16_f32 v99, v84, v85
	global_store_dwordx4 v[94:95], v[96:99], off sc1

.LBB0_349:
	v_cvt_pk_bf16_f32 v86, v86, v87
	v_cvt_pk_bf16_f32 v87, v88, v89
	v_cvt_pk_bf16_f32 v88, v92, v93
	v_cvt_pk_bf16_f32 v89, v84, v85
	v_mov_b32_e32 v84, v90
	v_mov_b32_e32 v85, v90
	v_mov_b32_e32 v91, v90
	v_pk_mul_f32 v[80:81], v[80:81], v[84:85]
	v_pk_mul_f32 v[76:77], v[76:77], v[84:85]
	v_lshl_add_u64 v[84:85], s[94:95], 0, v[0:1]
	v_mov_b32_e32 v155, v1
	v_pk_mul_f32 v[78:79], v[78:79], v[90:91]
	v_pk_mul_f32 v[74:75], v[74:75], v[90:91]
	s_and_b64 vcc, exec, s[52:53]
	v_lshl_add_u64 v[84:85], v[84:85], 0, v[154:155]
	global_store_dwordx4 v[96:97], v[86:89], off sc1
	s_cbranch_vccz .LBB0_424
	s_and_b64 vcc, exec, s[54:55]
	s_cbranch_vccz .LBB0_425

.LBB0_354:
	v_cvt_pk_bf16_f32 v78, v78, v79
	v_cvt_pk_bf16_f32 v79, v80, v81
	v_cvt_pk_bf16_f32 v80, v74, v75
	v_cvt_pk_bf16_f32 v81, v76, v77
	ds_read_b32 v74, v182 offset:512
	global_store_dwordx4 v[86:87], v[78:81], off sc1
	v_add_u32_e32 v86, 0x80, v185
	s_and_b64 vcc, exec, s[42:43]
	v_and_b32_e32 v0, 0x7cf, v86
	s_cbranch_vccnz .LBB0_356
	v_cvt_f32_u32_e32 v53, v0
	v_mul_f32_e32 v51, v178, v53
	v_mul_f32_e32 v52, v179, v53
	v_fract_f32_e32 v51, v51
	v_fract_f32_e32 v52, v52
	v_mul_f32_e32 v50, v174, v53
	v_cos_f32_e32 v156, v51
	v_sin_f32_e32 v54, v51
	v_mul_f32_e32 v51, v175, v53
	v_cos_f32_e32 v157, v52
	v_sin_f32_e32 v55, v52
	v_mul_f32_e32 v52, v176, v53
	v_mul_f32_e32 v56, v180, v53
	v_mul_f32_e32 v57, v177, v53
	v_mul_f32_e32 v75, v181, v53
	v_fract_f32_e32 v50, v50
	v_fract_f32_e32 v51, v51
	v_fract_f32_e32 v52, v52
	v_fract_f32_e32 v56, v56
	v_fract_f32_e32 v57, v57
	v_fract_f32_e32 v75, v75
	v_cos_f32_e32 v158, v50
	v_sin_f32_e32 v50, v50
	v_cos_f32_e32 v159, v51
	v_sin_f32_e32 v51, v51
	v_cos_f32_e32 v162, v52
	v_sin_f32_e32 v52, v52
	v_cos_f32_e32 v160, v56
	v_sin_f32_e32 v56, v56
	v_sin_f32_e32 v53, v57
	v_cos_f32_e32 v163, v57
	v_sin_f32_e32 v57, v75
	v_cos_f32_e32 v161, v75
	v_pk_mul_f32 v[52:53], v[148:149], v[52:53]
	v_pk_mul_f32 v[50:51], v[146:147], v[50:51]
	v_pk_mul_f32 v[56:57], v[148:149], v[56:57]
	v_pk_mul_f32 v[54:55], v[146:147], v[54:55]
.LBB0_356:
	v_ashrrev_i32_e32 v87, 11, v86
	s_waitcnt lgkmcnt(0)
	v_pk_mul_f32 v[80:81], v[66:67], v[74:75] op_sel_hi:[1,0]
	v_mov_b32_e32 v66, s65
	s_movk_i32 s4, 0x50
	v_pk_mul_f32 v[76:77], v[68:69], v[74:75] op_sel_hi:[1,0]
	v_mad_i32_i24 v68, v87, s4, v66
	v_ashrrev_i32_e32 v69, 31, v68
	v_lshlrev_b64 v[66:67], 19, v[68:69]
	v_lshlrev_b32_e32 v0, 8, v0
	v_lshl_add_u64 v[66:67], s[30:31], 0, v[66:67]
	v_pk_mul_f32 v[78:79], v[70:71], v[74:75] op_sel_hi:[1,0]
	v_lshl_add_u64 v[70:71], v[66:67], 0, v[0:1]
	v_mov_b32_e32 v155, v1
	v_pk_mul_f32 v[72:73], v[72:73], v[74:75] op_sel_hi:[1,0]
	s_and_b64 vcc, exec, s[46:47]
	v_lshl_add_u64 v[82:83], v[70:71], 0, v[154:155]
	s_cbranch_vccnz .LBB0_358
	v_cvt_pk_bf16_f32 v88, v78, v79
	v_cvt_pk_bf16_f32 v89, v72, v73
	v_cvt_pk_bf16_f32 v90, v80, v81
	v_cvt_pk_bf16_f32 v91, v76, v77
	global_store_dwordx4 v[82:83], v[88:91], off sc1

.LBB0_364:
	v_mul_i32_i24_e32 v82, 0x50, v87
	v_mov_b32_e32 v75, v74
	v_cvt_pk_bf16_f32 v78, v78, v79
	v_cvt_pk_bf16_f32 v79, v72, v73
	v_cvt_pk_bf16_f32 v80, v80, v81
	v_cvt_pk_bf16_f32 v81, v76, v77
	v_mov_b32_e32 v76, v74
	v_mov_b32_e32 v77, v74
	v_pk_mul_f32 v[72:73], v[62:63], v[74:75]
	v_pk_mul_f32 v[62:63], v[60:61], v[76:77]
	v_add_u32_e32 v60, s39, v82
	v_ashrrev_i32_e32 v61, 31, v60
	v_pk_mul_f32 v[74:75], v[58:59], v[74:75]
	v_lshlrev_b64 v[58:59], 19, v[60:61]
	v_lshl_add_u64 v[58:59], s[30:31], 0, v[58:59]
	v_pk_mul_f32 v[64:65], v[64:65], v[76:77]
	v_lshl_add_u64 v[76:77], v[58:59], 0, v[0:1]
	v_mov_b32_e32 v155, v1
	s_and_b64 vcc, exec, s[52:53]
	v_lshl_add_u64 v[76:77], v[76:77], 0, v[154:155]
	global_store_dwordx4 v[84:85], v[78:81], off sc1
	s_cbranch_vccz .LBB0_427
	s_and_b64 vcc, exec, s[54:55]
	s_cbranch_vccz .LBB0_428

.LBB0_370:
	v_cvt_pk_bf16_f32 v70, v72, v73
	v_cvt_pk_bf16_f32 v71, v64, v65
	v_cvt_pk_bf16_f32 v72, v74, v75
	v_cvt_pk_bf16_f32 v73, v62, v63
	ds_read_b32 v62, v182 offset:576
	s_movk_i32 s4, 0x7df
	s_and_b64 vcc, exec, s[42:43]
	v_bitop3_b32 v0, v86, s4, 16 bitop3:0xc8
	global_store_dwordx4 v[78:79], v[70:73], off sc1
	s_cbranch_vccnz .LBB0_372
	v_cvt_f32_u32_e32 v53, v0
	v_mul_f32_e32 v51, v178, v53
	v_mul_f32_e32 v52, v179, v53
	v_fract_f32_e32 v51, v51
	v_fract_f32_e32 v52, v52
	v_mul_f32_e32 v50, v174, v53
	v_cos_f32_e32 v156, v51
	v_sin_f32_e32 v54, v51
	v_mul_f32_e32 v51, v175, v53
	v_cos_f32_e32 v157, v52
	v_sin_f32_e32 v55, v52
	v_mul_f32_e32 v52, v176, v53
	v_mul_f32_e32 v56, v180, v53
	v_mul_f32_e32 v57, v177, v53
	v_mul_f32_e32 v63, v181, v53
	v_fract_f32_e32 v50, v50
	v_fract_f32_e32 v51, v51
	v_fract_f32_e32 v52, v52
	v_fract_f32_e32 v56, v56
	v_fract_f32_e32 v57, v57
	v_fract_f32_e32 v63, v63
	v_cos_f32_e32 v158, v50
	v_sin_f32_e32 v50, v50
	v_cos_f32_e32 v159, v51
	v_sin_f32_e32 v51, v51
	v_cos_f32_e32 v162, v52
	v_sin_f32_e32 v52, v52
	v_cos_f32_e32 v160, v56
	v_sin_f32_e32 v56, v56
	v_sin_f32_e32 v53, v57
	v_cos_f32_e32 v163, v57
	v_sin_f32_e32 v57, v63
	v_cos_f32_e32 v161, v63
	v_pk_mul_f32 v[52:53], v[148:149], v[52:53]
	v_pk_mul_f32 v[50:51], v[146:147], v[50:51]
	v_pk_mul_f32 v[56:57], v[148:149], v[56:57]
	v_pk_mul_f32 v[54:55], v[146:147], v[54:55]
.LBB0_372:
	v_lshlrev_b32_e32 v0, 8, v0
	s_waitcnt lgkmcnt(0)
	v_pk_mul_f32 v[64:65], v[42:43], v[62:63] op_sel_hi:[1,0]
	v_lshl_add_u64 v[42:43], v[66:67], 0, v[0:1]
	v_mov_b32_e32 v155, v1
	v_pk_mul_f32 v[48:49], v[48:49], v[62:63] op_sel_hi:[1,0]
	v_pk_mul_f32 v[46:47], v[46:47], v[62:63] op_sel_hi:[1,0]
	v_pk_mul_f32 v[44:45], v[44:45], v[62:63] op_sel_hi:[1,0]
	s_and_b64 vcc, exec, s[46:47]
	v_lshl_add_u64 v[70:71], v[42:43], 0, v[154:155]
	s_cbranch_vccnz .LBB0_374
	v_cvt_pk_bf16_f32 v72, v46, v47
	v_cvt_pk_bf16_f32 v73, v48, v49
	v_cvt_pk_bf16_f32 v74, v64, v65
	v_cvt_pk_bf16_f32 v75, v44, v45
	global_store_dwordx4 v[70:71], v[72:75], off sc1

.LBB0_380:
	v_cvt_pk_bf16_f32 v46, v46, v47
	v_cvt_pk_bf16_f32 v47, v48, v49
	v_cvt_pk_bf16_f32 v48, v64, v65
	v_cvt_pk_bf16_f32 v49, v44, v45
	v_mov_b32_e32 v44, v62
	v_mov_b32_e32 v45, v62
	v_mov_b32_e32 v63, v62
	v_pk_mul_f32 v[40:41], v[40:41], v[44:45]
	v_pk_mul_f32 v[36:37], v[36:37], v[44:45]
	v_lshl_add_u64 v[44:45], v[58:59], 0, v[0:1]
	v_mov_b32_e32 v155, v1
	v_pk_mul_f32 v[38:39], v[38:39], v[62:63]
	v_pk_mul_f32 v[34:35], v[34:35], v[62:63]
	s_and_b64 vcc, exec, s[52:53]
	v_lshl_add_u64 v[44:45], v[44:45], 0, v[154:155]
	global_store_dwordx4 v[72:73], v[46:49], off sc1
	s_cbranch_vccz .LBB0_429
	s_and_b64 vcc, exec, s[54:55]
	s_cbranch_vccz .LBB0_430

.LBB0_385:
	v_cvt_pk_bf16_f32 v38, v38, v39
	v_cvt_pk_bf16_f32 v39, v40, v41
	v_cvt_pk_bf16_f32 v40, v34, v35
	v_cvt_pk_bf16_f32 v41, v36, v37
	ds_read_b32 v34, v182 offset:640
	s_movk_i32 s4, 0x7ef
	s_and_b64 vcc, exec, s[42:43]
	v_bitop3_b32 v0, v86, s4, 32 bitop3:0xc8
	global_store_dwordx4 v[46:47], v[38:41], off sc1
	s_cbranch_vccnz .LBB0_387
	v_cvt_f32_u32_e32 v35, v0
	v_mul_f32_e32 v37, v178, v35
	v_mul_f32_e32 v41, v180, v35
	v_fract_f32_e32 v37, v37
	v_fract_f32_e32 v41, v41
	v_mul_f32_e32 v36, v174, v35
	v_cos_f32_e32 v156, v37
	v_sin_f32_e32 v38, v37
	v_mul_f32_e32 v37, v175, v35
	v_mul_f32_e32 v39, v179, v35
	v_mul_f32_e32 v40, v176, v35
	v_cos_f32_e32 v160, v41
	v_sin_f32_e32 v42, v41
	v_mul_f32_e32 v41, v177, v35
	v_mul_f32_e32 v35, v181, v35
	v_fract_f32_e32 v36, v36
	v_fract_f32_e32 v37, v37
	v_fract_f32_e32 v39, v39
	v_fract_f32_e32 v40, v40
	v_fract_f32_e32 v43, v41
	v_fract_f32_e32 v35, v35
	v_cos_f32_e32 v158, v36
	v_sin_f32_e32 v36, v36
	v_cos_f32_e32 v159, v37
	v_sin_f32_e32 v37, v37
	v_cos_f32_e32 v157, v39
	v_sin_f32_e32 v39, v39
	v_cos_f32_e32 v162, v40
	v_sin_f32_e32 v40, v40
	v_sin_f32_e32 v41, v43
	v_cos_f32_e32 v163, v43
	v_sin_f32_e32 v43, v35
	v_cos_f32_e32 v161, v35
	v_pk_mul_f32 v[52:53], v[148:149], v[40:41]
	v_pk_mul_f32 v[50:51], v[146:147], v[36:37]
	v_pk_mul_f32 v[56:57], v[148:149], v[42:43]
	v_pk_mul_f32 v[54:55], v[146:147], v[38:39]
.LBB0_387:
	v_lshlrev_b32_e32 v0, 8, v0
	s_waitcnt lgkmcnt(0)
	v_pk_mul_f32 v[36:37], v[26:27], v[34:35] op_sel_hi:[1,0]
	v_lshl_add_u64 v[26:27], v[66:67], 0, v[0:1]
	v_mov_b32_e32 v155, v1
	v_pk_mul_f32 v[32:33], v[32:33], v[34:35] op_sel_hi:[1,0]
	v_pk_mul_f32 v[30:31], v[30:31], v[34:35] op_sel_hi:[1,0]
	v_pk_mul_f32 v[28:29], v[28:29], v[34:35] op_sel_hi:[1,0]
	s_and_b64 vcc, exec, s[46:47]
	v_lshl_add_u64 v[38:39], v[26:27], 0, v[154:155]
	s_cbranch_vccnz .LBB0_389
	v_cvt_pk_bf16_f32 v40, v30, v31
	v_cvt_pk_bf16_f32 v41, v32, v33
	v_cvt_pk_bf16_f32 v42, v36, v37
	v_cvt_pk_bf16_f32 v43, v28, v29
	global_store_dwordx4 v[38:39], v[40:43], off sc1

.LBB0_395:
	v_cvt_pk_bf16_f32 v30, v30, v31
	v_cvt_pk_bf16_f32 v31, v32, v33
	v_cvt_pk_bf16_f32 v32, v36, v37
	v_cvt_pk_bf16_f32 v33, v28, v29
	v_mov_b32_e32 v28, v34
	v_mov_b32_e32 v29, v34
	v_mov_b32_e32 v35, v34
	v_pk_mul_f32 v[24:25], v[24:25], v[28:29]
	v_pk_mul_f32 v[20:21], v[20:21], v[28:29]
	v_lshl_add_u64 v[28:29], v[58:59], 0, v[0:1]
	v_mov_b32_e32 v155, v1
	v_pk_mul_f32 v[22:23], v[22:23], v[34:35]
	v_pk_mul_f32 v[18:19], v[18:19], v[34:35]
	s_and_b64 vcc, exec, s[52:53]
	v_lshl_add_u64 v[28:29], v[28:29], 0, v[154:155]
	global_store_dwordx4 v[40:41], v[30:33], off sc1
	s_cbranch_vccz .LBB0_432
	s_and_b64 vcc, exec, s[54:55]
	s_cbranch_vccz .LBB0_433

.LBB0_400:
	v_cvt_pk_bf16_f32 v22, v22, v23
	v_cvt_pk_bf16_f32 v23, v24, v25
	v_cvt_pk_bf16_f32 v24, v18, v19
	v_cvt_pk_bf16_f32 v25, v20, v21
	ds_read_b32 v18, v182 offset:704
	s_and_b64 vcc, exec, s[42:43]
	v_bitop3_b32 v0, v86, s91, 48 bitop3:0xc8
	global_store_dwordx4 v[30:31], v[22:25], off sc1
	s_cbranch_vccnz .LBB0_402
	v_cvt_f32_u32_e32 v19, v0
	v_mul_f32_e32 v21, v178, v19
	v_mul_f32_e32 v25, v180, v19
	v_fract_f32_e32 v21, v21
	v_fract_f32_e32 v25, v25
	v_mul_f32_e32 v20, v174, v19
	v_cos_f32_e32 v156, v21
	v_sin_f32_e32 v22, v21
	v_mul_f32_e32 v21, v175, v19
	v_mul_f32_e32 v23, v179, v19
	v_mul_f32_e32 v24, v176, v19
	v_cos_f32_e32 v160, v25
	v_sin_f32_e32 v26, v25
	v_mul_f32_e32 v25, v177, v19
	v_mul_f32_e32 v19, v181, v19
	v_fract_f32_e32 v20, v20
	v_fract_f32_e32 v21, v21
	v_fract_f32_e32 v23, v23
	v_fract_f32_e32 v24, v24
	v_fract_f32_e32 v27, v25
	v_fract_f32_e32 v19, v19
	v_cos_f32_e32 v158, v20
	v_sin_f32_e32 v20, v20
	v_cos_f32_e32 v159, v21
	v_sin_f32_e32 v21, v21
	v_cos_f32_e32 v157, v23
	v_sin_f32_e32 v23, v23
	v_cos_f32_e32 v162, v24
	v_sin_f32_e32 v24, v24
	v_sin_f32_e32 v25, v27
	v_cos_f32_e32 v163, v27
	v_sin_f32_e32 v27, v19
	v_cos_f32_e32 v161, v19
	v_pk_mul_f32 v[52:53], v[148:149], v[24:25]
	v_pk_mul_f32 v[50:51], v[146:147], v[20:21]
	v_pk_mul_f32 v[56:57], v[148:149], v[26:27]
	v_pk_mul_f32 v[54:55], v[146:147], v[22:23]
.LBB0_402:
	v_lshlrev_b32_e32 v0, 8, v0
	s_waitcnt lgkmcnt(0)
	v_pk_mul_f32 v[20:21], v[10:11], v[18:19] op_sel_hi:[1,0]
	v_lshl_add_u64 v[10:11], v[66:67], 0, v[0:1]
	v_mov_b32_e32 v155, v1
	v_pk_mul_f32 v[16:17], v[16:17], v[18:19] op_sel_hi:[1,0]
	v_pk_mul_f32 v[14:15], v[14:15], v[18:19] op_sel_hi:[1,0]
	v_pk_mul_f32 v[12:13], v[12:13], v[18:19] op_sel_hi:[1,0]
	s_and_b64 vcc, exec, s[46:47]
	v_lshl_add_u64 v[22:23], v[10:11], 0, v[154:155]
	s_cbranch_vccnz .LBB0_404
	v_cvt_pk_bf16_f32 v24, v14, v15
	v_cvt_pk_bf16_f32 v25, v16, v17
	v_cvt_pk_bf16_f32 v26, v20, v21
	v_cvt_pk_bf16_f32 v27, v12, v13
	global_store_dwordx4 v[22:23], v[24:27], off sc1

.LBB0_410:
	v_cvt_pk_bf16_f32 v14, v14, v15
	v_cvt_pk_bf16_f32 v15, v16, v17
	v_cvt_pk_bf16_f32 v16, v20, v21
	v_cvt_pk_bf16_f32 v17, v12, v13
	v_mov_b32_e32 v12, v18
	v_mov_b32_e32 v13, v18
	v_mov_b32_e32 v19, v18
	v_pk_mul_f32 v[8:9], v[8:9], v[12:13]
	v_pk_mul_f32 v[4:5], v[4:5], v[12:13]
	v_lshl_add_u64 v[12:13], v[58:59], 0, v[0:1]
	v_mov_b32_e32 v155, v1
	v_pk_mul_f32 v[6:7], v[6:7], v[18:19]
	v_pk_mul_f32 v[2:3], v[2:3], v[18:19]
	s_and_b64 vcc, exec, s[52:53]
	v_lshl_add_u64 v[12:13], v[12:13], 0, v[154:155]
	global_store_dwordx4 v[24:25], v[14:17], off sc1
	s_cbranch_vccz .LBB0_435
	s_and_b64 vcc, exec, s[54:55]
	s_cbranch_vccz .LBB0_436

.LBB0_415:
	s_andn2_b64 vcc, exec, s[40:41]
	s_mov_b64 s[4:5], -1
	v_cvt_pk_bf16_f32 v6, v6, v7
	v_cvt_pk_bf16_f32 v7, v8, v9
	v_cvt_pk_bf16_f32 v8, v2, v3
	v_cvt_pk_bf16_f32 v9, v4, v5
	global_store_dwordx4 v[14:15], v[6:9], off sc1
	s_cbranch_vccnz .LBB0_280
	s_andn2_b64 vcc, exec, s[18:19]
	s_cbranch_vccnz .LBB0_279
	s_barrier
	s_branch .LBB0_279
.LBB0_418:
	s_nop 0
	v_cvt_pk_bf16_f32 v118, v110, v111
	v_cvt_pk_bf16_f32 v119, v112, v113
	v_cvt_pk_bf16_f32 v120, v106, v107
	v_cvt_pk_bf16_f32 v121, v108, v109
	global_store_dwordx4 v[116:117], v[118:121], off sc1
	s_and_b64 vcc, exec, s[54:55]
	s_cbranch_vccnz .LBB0_321

.LBB0_421:
	s_nop 0
	v_cvt_pk_bf16_f32 v102, v94, v95
	v_cvt_pk_bf16_f32 v103, v96, v97
	v_cvt_pk_bf16_f32 v104, v90, v91
	v_cvt_pk_bf16_f32 v105, v92, v93
	global_store_dwordx4 v[100:101], v[102:105], off sc1
	s_and_b64 vcc, exec, s[54:55]
	s_cbranch_vccnz .LBB0_336

.LBB0_424:
	s_nop 0
	v_cvt_pk_bf16_f32 v86, v78, v79
	v_cvt_pk_bf16_f32 v87, v80, v81
	v_cvt_pk_bf16_f32 v88, v74, v75
	v_cvt_pk_bf16_f32 v89, v76, v77
	global_store_dwordx4 v[84:85], v[86:89], off sc1
	s_and_b64 vcc, exec, s[54:55]
	s_cbranch_vccnz .LBB0_351

.LBB0_427:
	s_nop 0
	v_cvt_pk_bf16_f32 v78, v72, v73
	v_cvt_pk_bf16_f32 v79, v64, v65
	v_cvt_pk_bf16_f32 v80, v74, v75
	v_cvt_pk_bf16_f32 v81, v62, v63
	global_store_dwordx4 v[76:77], v[78:81], off sc1
	s_and_b64 vcc, exec, s[54:55]
	s_cbranch_vccnz .LBB0_366

.LBB0_429:
	s_nop 0
	v_cvt_pk_bf16_f32 v46, v38, v39
	v_cvt_pk_bf16_f32 v47, v40, v41
	v_cvt_pk_bf16_f32 v48, v34, v35
	v_cvt_pk_bf16_f32 v49, v36, v37
	global_store_dwordx4 v[44:45], v[46:49], off sc1
	s_and_b64 vcc, exec, s[54:55]
	s_cbranch_vccnz .LBB0_382

.LBB0_432:
	s_nop 0
	v_cvt_pk_bf16_f32 v30, v22, v23
	v_cvt_pk_bf16_f32 v31, v24, v25
	v_cvt_pk_bf16_f32 v32, v18, v19
	v_cvt_pk_bf16_f32 v33, v20, v21
	global_store_dwordx4 v[28:29], v[30:33], off sc1
	s_and_b64 vcc, exec, s[54:55]
	s_cbranch_vccnz .LBB0_397

.LBB0_435:
	s_nop 0
	v_cvt_pk_bf16_f32 v14, v6, v7
	v_cvt_pk_bf16_f32 v15, v8, v9
	v_cvt_pk_bf16_f32 v16, v2, v3
	v_cvt_pk_bf16_f32 v17, v4, v5
	global_store_dwordx4 v[12:13], v[14:17], off sc1
	s_and_b64 vcc, exec, s[54:55]
	s_cbranch_vccnz .LBB0_412
